# copy engines stop grabbing once 16 workgroups have arrived at the coming grid barrier (phase and tail engines)
# baseline (speedup 1.0000x reference)
.LBB0_184:
	v_mov_b32_e32 v31, -1
	s_mov_b64 s[0:1], exec
	v_readlane_b32 s2, v242, 26
	v_readlane_b32 s3, v242, 27
	s_and_b64 s[2:3], s[0:1], s[2:3]
	s_mov_b64 exec, s[2:3]
	s_cbranch_execz .LBB0_189
	v_readlane_b32 s2, v241, 2
	v_readlane_b32 s3, v241, 3
	v_mov_b32_e32 v31, -1
	s_nop 3
	global_load_dword v2, v1, s[2:3] sc1
	v_readlane_b32 s2, v241, 4
	v_readlane_b32 s3, v241, 5
	s_nop 4
	global_load_dword v3, v1, s[2:3] sc1
	v_readlane_b32 s2, v241, 6
	v_readlane_b32 s3, v241, 7
	s_nop 4
	global_load_dword v4, v1, s[2:3] sc1
	v_readlane_b32 s2, v241, 8
	v_readlane_b32 s3, v241, 9
	s_nop 4
	global_load_dword v5, v1, s[2:3] sc1
	v_readlane_b32 s2, v241, 10
	v_readlane_b32 s3, v241, 11
	s_nop 4
	global_load_dword v6, v1, s[2:3] sc1
	v_readlane_b32 s2, v241, 12
	v_readlane_b32 s3, v241, 13
	s_nop 4
	global_load_dword v7, v1, s[2:3] sc1
	global_load_dword v8, v1, s[34:35] sc1
	global_load_dword v9, v1, s[40:41] sc1
	global_load_dword v10, v1, s[42:43] sc1
	global_load_dword v11, v1, s[50:51] sc1
	global_load_dword v12, v1, s[56:57] sc1
	global_load_dword v13, v1, s[60:61] sc1
	global_load_dword v14, v1, s[62:63] sc1
	global_load_dword v15, v1, s[64:65] sc1
	global_load_dword v16, v1, s[68:69] sc1
	global_load_dword v17, v1, s[70:71] sc1
	v_readlane_b32 s2, v242, 25
	s_mul_i32 s2, s84, s2
	s_waitcnt vmcnt(15)
	v_subrev_u32_e32 v2, s2, v2
	s_waitcnt vmcnt(14)
	v_add_u32_e32 v2, v2, v3
	s_waitcnt vmcnt(13)
	v_add_u32_e32 v2, v2, v4
	s_waitcnt vmcnt(12)
	v_add_u32_e32 v2, v2, v5
	s_waitcnt vmcnt(11)
	v_add_u32_e32 v2, v2, v6
	s_waitcnt vmcnt(10)
	v_add_u32_e32 v2, v2, v7
	s_waitcnt vmcnt(9)
	v_add_u32_e32 v2, v2, v8
	s_waitcnt vmcnt(8)
	v_add_u32_e32 v2, v2, v9
	s_waitcnt vmcnt(7)
	v_add_u32_e32 v2, v2, v10
	s_waitcnt vmcnt(6)
	v_add_u32_e32 v2, v2, v11
	s_waitcnt vmcnt(5)
	v_add_u32_e32 v2, v2, v12
	s_waitcnt vmcnt(4)
	v_add_u32_e32 v2, v2, v13
	s_waitcnt vmcnt(3)
	v_add_u32_e32 v2, v2, v14
	s_waitcnt vmcnt(2)
	v_add_u32_e32 v2, v2, v15
	s_waitcnt vmcnt(1)
	v_add_u32_e32 v2, v2, v16
	s_waitcnt vmcnt(0)
	v_add_u32_e32 v2, v2, v17
	v_cmp_le_u32_e32 vcc, 16, v2
	s_cbranch_vccnz .LBB0_189
	s_mov_b64 s[6:7], exec
	v_mbcnt_lo_u32_b32 v2, s6, 0
	v_mbcnt_hi_u32_b32 v2, s7, v2
	v_cmp_eq_u32_e32 vcc, 0, v2
	s_and_saveexec_b64 s[2:3], vcc
	s_cbranch_execz .LBB0_188
	s_bcnt1_i32_b64 s4, s[6:7]
	s_lshl_b32 s4, s4, 3
	v_readlane_b32 s6, v242, 43
	v_mov_b32_e32 v3, s4
	v_readlane_b32 s7, v242, 44
	s_nop 4
	global_atomic_add v3, v1, v3, s[6:7] sc0

.LBB0_527:
	v_mov_b32_e32 v31, -1
	s_mov_b64 s[0:1], exec
	v_readlane_b32 s2, v242, 26
	v_readlane_b32 s3, v242, 27
	s_and_b64 s[2:3], s[0:1], s[2:3]
	s_mov_b64 exec, s[2:3]
	s_cbranch_execz .LBB0_532
	v_readlane_b32 s2, v241, 2
	v_readlane_b32 s3, v241, 3
	v_mov_b32_e32 v31, -1
	s_nop 3
	global_load_dword v2, v1, s[2:3] sc1
	v_readlane_b32 s2, v241, 4
	v_readlane_b32 s3, v241, 5
	s_waitcnt vmcnt(0)
	v_subrev_u32_e32 v2, s55, v2
	s_nop 2
	global_load_dword v3, v1, s[2:3] sc1
	v_readlane_b32 s2, v241, 6
	v_readlane_b32 s3, v241, 7
	s_waitcnt vmcnt(0)
	v_add_u32_e32 v2, v2, v3
	s_nop 2
	global_load_dword v4, v1, s[2:3] sc1
	v_readlane_b32 s2, v241, 8
	v_readlane_b32 s3, v241, 9
	s_waitcnt vmcnt(0)
	v_add_u32_e32 v2, v2, v4
	s_nop 2
	global_load_dword v5, v1, s[2:3] sc1
	v_readlane_b32 s2, v241, 10
	v_readlane_b32 s3, v241, 11
	s_waitcnt vmcnt(0)
	v_add_u32_e32 v2, v2, v5
	s_nop 2
	global_load_dword v6, v1, s[2:3] sc1
	v_readlane_b32 s2, v241, 12
	v_readlane_b32 s3, v241, 13
	s_nop 4
	global_load_dword v7, v1, s[2:3] sc1
	global_load_dword v8, v1, s[34:35] sc1
	global_load_dword v9, v1, s[40:41] sc1
	global_load_dword v10, v1, s[42:43] sc1
	global_load_dword v11, v1, s[50:51] sc1
	global_load_dword v12, v1, s[56:57] sc1
	global_load_dword v13, v1, s[60:61] sc1
	global_load_dword v14, v1, s[62:63] sc1
	global_load_dword v15, v1, s[64:65] sc1
	global_load_dword v16, v1, s[68:69] sc1
	global_load_dword v17, v1, s[70:71] sc1
	s_movk_i32 s2, 0xf
	s_waitcnt vmcnt(11)
	v_add_u32_e32 v2, v2, v6
	s_waitcnt vmcnt(10)
	v_add_u32_e32 v2, v2, v7
	s_waitcnt vmcnt(9)
	v_add_u32_e32 v2, v2, v8
	s_waitcnt vmcnt(8)
	v_add_u32_e32 v2, v2, v9
	s_waitcnt vmcnt(7)
	v_add_u32_e32 v2, v2, v10
	s_waitcnt vmcnt(6)
	v_add_u32_e32 v2, v2, v11
	s_waitcnt vmcnt(5)
	v_add_u32_e32 v2, v2, v12
	s_waitcnt vmcnt(4)
	v_add_u32_e32 v2, v2, v13
	s_waitcnt vmcnt(3)
	v_add_u32_e32 v2, v2, v14
	s_waitcnt vmcnt(2)
	v_add_u32_e32 v2, v2, v15
	s_waitcnt vmcnt(1)
	v_add_u32_e32 v2, v2, v16
	s_waitcnt vmcnt(0)
	v_add_u32_e32 v2, v2, v17
	v_cmp_lt_u32_e32 vcc, s2, v2
	s_cbranch_vccnz .LBB0_532
	s_mov_b64 s[6:7], exec
	v_mbcnt_lo_u32_b32 v2, s6, 0
	v_mbcnt_hi_u32_b32 v2, s7, v2
	v_cmp_eq_u32_e32 vcc, 0, v2
	s_and_saveexec_b64 s[2:3], vcc
	s_cbranch_execz .LBB0_531
	s_bcnt1_i32_b64 s4, s[6:7]
	s_lshl_b32 s4, s4, 3
	v_readlane_b32 s6, v242, 43
	v_mov_b32_e32 v3, s4
	v_readlane_b32 s7, v242, 44
	s_nop 4
	global_atomic_add v3, v1, v3, s[6:7] sc0

.LBB0_1761:
	v_mov_b32_e32 v31, -1
	s_mov_b64 s[48:49], exec
	v_readlane_b32 s0, v242, 26
	v_readlane_b32 s1, v242, 27
	s_and_b64 s[0:1], s[48:49], s[0:1]
	s_mov_b64 exec, s[0:1]
	s_cbranch_execz .LBB0_1766
	v_readlane_b32 s0, v242, 30
	v_readlane_b32 s1, v242, 31
	v_mov_b32_e32 v31, -1
	s_nop 3
	global_load_dword v2, v1, s[0:1] sc1
	v_readlane_b32 s0, v241, 2
	v_readlane_b32 s1, v241, 3
	s_nop 4
	global_load_dword v3, v1, s[0:1] sc1
	v_readlane_b32 s0, v241, 4
	v_readlane_b32 s1, v241, 5
	s_nop 4
	global_load_dword v4, v1, s[0:1] sc1
	v_readlane_b32 s0, v241, 6
	v_readlane_b32 s1, v241, 7
	s_nop 4
	global_load_dword v5, v1, s[0:1] sc1
	v_readlane_b32 s0, v241, 8
	v_readlane_b32 s1, v241, 9
	s_nop 4
	global_load_dword v6, v1, s[0:1] sc1
	global_load_dword v7, v1, s[14:15] sc1
	global_load_dword v8, v1, s[16:17] sc1
	global_load_dword v9, v1, s[18:19] sc1
	global_load_dword v10, v1, s[20:21] sc1
	global_load_dword v11, v1, s[22:23] sc1
	global_load_dword v12, v1, s[24:25] sc1
	global_load_dword v13, v1, s[26:27] sc1
	global_load_dword v14, v1, s[28:29] sc1
	global_load_dword v15, v1, s[30:31] sc1
	global_load_dword v16, v1, s[34:35] sc1
	global_load_dword v17, v1, s[40:41] sc1
	v_readlane_b32 s0, v242, 25
	s_mul_i32 s0, s84, s0
	s_waitcnt vmcnt(15)
	v_subrev_u32_e32 v2, s0, v2
	s_waitcnt vmcnt(14)
	v_add_u32_e32 v2, v2, v3
	s_waitcnt vmcnt(13)
	v_add_u32_e32 v2, v2, v4
	s_waitcnt vmcnt(12)
	v_add_u32_e32 v2, v2, v5
	s_waitcnt vmcnt(11)
	v_add_u32_e32 v2, v2, v6
	s_waitcnt vmcnt(10)
	v_add_u32_e32 v2, v2, v7
	s_waitcnt vmcnt(9)
	v_add_u32_e32 v2, v2, v8
	s_waitcnt vmcnt(8)
	v_add_u32_e32 v2, v2, v9
	s_waitcnt vmcnt(7)
	v_add_u32_e32 v2, v2, v10
	s_waitcnt vmcnt(6)
	v_add_u32_e32 v2, v2, v11
	s_waitcnt vmcnt(5)
	v_add_u32_e32 v2, v2, v12
	s_waitcnt vmcnt(4)
	v_add_u32_e32 v2, v2, v13
	s_waitcnt vmcnt(3)
	v_add_u32_e32 v2, v2, v14
	s_waitcnt vmcnt(2)
	v_add_u32_e32 v2, v2, v15
	s_waitcnt vmcnt(1)
	v_add_u32_e32 v2, v2, v16
	s_waitcnt vmcnt(0)
	v_add_u32_e32 v2, v2, v17
	v_cmp_le_u32_e32 vcc, 16, v2
	s_cbranch_vccnz .LBB0_1766
	s_mov_b64 s[52:53], exec
	v_mbcnt_lo_u32_b32 v2, s52, 0
	v_mbcnt_hi_u32_b32 v2, s53, v2
	v_cmp_eq_u32_e32 vcc, 0, v2
	s_and_saveexec_b64 s[50:51], vcc
	s_cbranch_execz .LBB0_1765
	s_bcnt1_i32_b64 s0, s[52:53]
	s_lshl_b32 s0, s0, 3
	v_mov_b32_e32 v3, s0
	v_readlane_b32 s0, v242, 43
	v_readlane_b32 s1, v242, 44
	s_nop 4
	global_atomic_add v3, v1, v3, s[0:1] sc0

.LBB0_1966:
	v_mov_b32_e32 v31, -1
	s_mov_b64 s[42:43], exec
	v_readlane_b32 s0, v242, 26
	v_readlane_b32 s1, v242, 27
	s_and_b64 s[0:1], s[42:43], s[0:1]
	s_mov_b64 exec, s[0:1]
	s_cbranch_execz .LBB0_1971
	v_readlane_b32 s0, v242, 30
	v_readlane_b32 s1, v242, 31
	v_mov_b32_e32 v31, -1
	s_nop 3
	global_load_dword v2, v1, s[0:1] sc1
	v_readlane_b32 s0, v241, 2
	v_readlane_b32 s1, v241, 3
	s_nop 4
	global_load_dword v3, v1, s[0:1] sc1
	v_readlane_b32 s0, v241, 4
	v_readlane_b32 s1, v241, 5
	s_nop 4
	global_load_dword v4, v1, s[0:1] sc1
	v_readlane_b32 s0, v241, 6
	v_readlane_b32 s1, v241, 7
	s_nop 4
	global_load_dword v5, v1, s[0:1] sc1
	global_load_dword v6, v1, s[14:15] sc1
	global_load_dword v7, v1, s[16:17] sc1
	global_load_dword v8, v1, s[18:19] sc1
	global_load_dword v9, v1, s[20:21] sc1
	global_load_dword v10, v1, s[22:23] sc1
	global_load_dword v11, v1, s[24:25] sc1
	global_load_dword v12, v1, s[26:27] sc1
	global_load_dword v13, v1, s[28:29] sc1
	global_load_dword v14, v1, s[30:31] sc1
	global_load_dword v15, v1, s[34:35] sc1
	global_load_dword v16, v1, s[36:37] sc1
	global_load_dword v17, v1, s[38:39] sc1
	v_readlane_b32 s0, v242, 25
	s_mul_i32 s0, s84, s0
	s_waitcnt vmcnt(15)
	v_subrev_u32_e32 v2, s0, v2
	s_waitcnt vmcnt(14)
	v_add_u32_e32 v2, v2, v3
	s_waitcnt vmcnt(13)
	v_add_u32_e32 v2, v2, v4
	s_waitcnt vmcnt(12)
	v_add_u32_e32 v2, v2, v5
	s_waitcnt vmcnt(11)
	v_add_u32_e32 v2, v2, v6
	s_waitcnt vmcnt(10)
	v_add_u32_e32 v2, v2, v7
	s_waitcnt vmcnt(9)
	v_add_u32_e32 v2, v2, v8
	s_waitcnt vmcnt(8)
	v_add_u32_e32 v2, v2, v9
	s_waitcnt vmcnt(7)
	v_add_u32_e32 v2, v2, v10
	s_waitcnt vmcnt(6)
	v_add_u32_e32 v2, v2, v11
	s_waitcnt vmcnt(5)
	v_add_u32_e32 v2, v2, v12
	s_waitcnt vmcnt(4)
	v_add_u32_e32 v2, v2, v13
	s_waitcnt vmcnt(3)
	v_add_u32_e32 v2, v2, v14
	s_waitcnt vmcnt(2)
	v_add_u32_e32 v2, v2, v15
	s_waitcnt vmcnt(1)
	v_add_u32_e32 v2, v2, v16
	s_waitcnt vmcnt(0)
	v_add_u32_e32 v2, v2, v17
	v_cmp_le_u32_e32 vcc, 16, v2
	s_cbranch_vccnz .LBB0_1971
	s_mov_b64 s[50:51], exec
	v_mbcnt_lo_u32_b32 v2, s50, 0
	v_mbcnt_hi_u32_b32 v2, s51, v2
	v_cmp_eq_u32_e32 vcc, 0, v2
	s_and_saveexec_b64 s[48:49], vcc
	s_cbranch_execz .LBB0_1970
	s_bcnt1_i32_b64 s0, s[50:51]
	s_lshl_b32 s0, s0, 3
	v_mov_b32_e32 v3, s0
	v_readlane_b32 s0, v242, 43
	v_readlane_b32 s1, v242, 44
	s_nop 4
	global_atomic_add v3, v1, v3, s[0:1] sc0

.LBB0_2017:
	v_mov_b32_e32 v31, -1
	s_mov_b64 s[42:43], exec
	v_readlane_b32 s0, v242, 26
	v_readlane_b32 s1, v242, 27
	s_and_b64 s[0:1], s[42:43], s[0:1]
	s_mov_b64 exec, s[0:1]
	s_cbranch_execz .LBB0_2022
	v_readlane_b32 s0, v242, 30
	v_readlane_b32 s1, v242, 31
	v_mov_b32_e32 v31, -1
	s_nop 3
	global_load_dword v2, v1, s[0:1] sc1
	v_readlane_b32 s0, v241, 2
	v_readlane_b32 s1, v241, 3
	s_waitcnt vmcnt(0)
	v_subrev_u32_e32 v2, s41, v2
	s_nop 2
	global_load_dword v3, v1, s[0:1] sc1
	v_readlane_b32 s0, v241, 4
	v_readlane_b32 s1, v241, 5
	s_waitcnt vmcnt(0)
	v_add_u32_e32 v2, v2, v3
	s_nop 2
	global_load_dword v4, v1, s[0:1] sc1
	v_readlane_b32 s0, v241, 6
	v_readlane_b32 s1, v241, 7
	s_nop 4
	global_load_dword v5, v1, s[0:1] sc1
	global_load_dword v6, v1, s[14:15] sc1
	global_load_dword v7, v1, s[16:17] sc1
	global_load_dword v8, v1, s[18:19] sc1
	global_load_dword v9, v1, s[20:21] sc1
	global_load_dword v10, v1, s[22:23] sc1
	global_load_dword v11, v1, s[24:25] sc1
	global_load_dword v12, v1, s[26:27] sc1
	global_load_dword v13, v1, s[28:29] sc1
	global_load_dword v14, v1, s[30:31] sc1
	global_load_dword v15, v1, s[34:35] sc1
	global_load_dword v16, v1, s[36:37] sc1
	global_load_dword v17, v1, s[38:39] sc1
	s_movk_i32 s0, 0xf
	s_waitcnt vmcnt(13)
	v_add_u32_e32 v2, v2, v4
	s_waitcnt vmcnt(12)
	v_add_u32_e32 v2, v2, v5
	s_waitcnt vmcnt(11)
	v_add_u32_e32 v2, v2, v6
	s_waitcnt vmcnt(10)
	v_add_u32_e32 v2, v2, v7
	s_waitcnt vmcnt(9)
	v_add_u32_e32 v2, v2, v8
	s_waitcnt vmcnt(8)
	v_add_u32_e32 v2, v2, v9
	s_waitcnt vmcnt(7)
	v_add_u32_e32 v2, v2, v10
	s_waitcnt vmcnt(6)
	v_add_u32_e32 v2, v2, v11
	s_waitcnt vmcnt(5)
	v_add_u32_e32 v2, v2, v12
	s_waitcnt vmcnt(4)
	v_add_u32_e32 v2, v2, v13
	s_waitcnt vmcnt(3)
	v_add_u32_e32 v2, v2, v14
	s_waitcnt vmcnt(2)
	v_add_u32_e32 v2, v2, v15
	s_waitcnt vmcnt(1)
	v_add_u32_e32 v2, v2, v16
	s_waitcnt vmcnt(0)
	v_add_u32_e32 v2, v2, v17
	v_cmp_lt_u32_e32 vcc, s0, v2
	s_cbranch_vccnz .LBB0_2022
	s_mov_b64 s[50:51], exec
	v_mbcnt_lo_u32_b32 v2, s50, 0
	v_mbcnt_hi_u32_b32 v2, s51, v2
	v_cmp_eq_u32_e32 vcc, 0, v2
	s_and_saveexec_b64 s[48:49], vcc
	s_cbranch_execz .LBB0_2021
	s_bcnt1_i32_b64 s0, s[50:51]
	s_lshl_b32 s0, s0, 3
	v_mov_b32_e32 v3, s0
	v_readlane_b32 s0, v242, 43
	v_readlane_b32 s1, v242, 44
	s_nop 4
	global_atomic_add v3, v1, v3, s[0:1] sc0
